# S2: L2 prefetch of the first unit's gate bytes before the stage's quad_wait (on top of mid2)
# baseline (speedup 1.0000x reference)
.LBB0_785:
	s_or_b64 exec, exec, s[2:3]
	s_cmp_lt_i32 s88, 5
	s_cselect_b64 s[0:1], -1, 0
	s_cmp_gt_i32 s89, 4
	s_cselect_b64 s[2:3], -1, 0
	s_and_b64 s[0:1], s[0:1], s[2:3]
	s_andn2_b64 vcc, exec, s[0:1]
	s_cbranch_vccnz .LBB0_869
	v_cmp_lt_u32_e32 vcc, 63, v0
	s_and_saveexec_b64 s[100:101], vcc
	s_ashr_i32 s98, s86, 1
	s_and_b32 s98, s98, -2
	s_lshl_b32 s98, s98, 19
	s_and_b32 s99, s86, 3
	s_lshl_b32 s99, s99, 8
	s_add_u32 s98, s98, s99
	v_readlane_b32 s99, v246, 2
	s_nop 3
	s_add_u32 s98, s98, s99
	v_readlane_b32 s99, v246, 3
	s_nop 3
	s_addc_u32 s99, s99, 0
	s_add_u32 s98, s98, 0xb600000
	s_addc_u32 s99, s99, 0
	v_add_u32_e32 v248, -64, v0
	v_mov_b32_e32 v249, v248
	v_min_u32_e32 v249, 0x3ff, v249
	v_lshrrev_b32_e32 v250, 2, v249
	v_lshlrev_b32_e32 v250, 11, v250
	v_bfe_u32 v251, v249, 1, 1
	v_and_b32_e32 v249, 1, v249
	v_lshl_or_b32 v250, v251, 10, v250
	v_lshl_or_b32 v250, v249, 7, v250
	global_load_dword v252, v250, s[98:99]
	v_add_u32_e32 v249, 448, v248
	v_min_u32_e32 v249, 0x3ff, v249
	v_lshrrev_b32_e32 v250, 2, v249
	v_lshlrev_b32_e32 v250, 11, v250
	v_bfe_u32 v251, v249, 1, 1
	v_and_b32_e32 v249, 1, v249
	v_lshl_or_b32 v250, v251, 10, v250
	v_lshl_or_b32 v250, v249, 7, v250
	global_load_dword v253, v250, s[98:99]
	v_add_u32_e32 v249, 896, v248
	v_min_u32_e32 v249, 0x3ff, v249
	v_lshrrev_b32_e32 v250, 2, v249
	v_lshlrev_b32_e32 v250, 11, v250
	v_bfe_u32 v251, v249, 1, 1
	v_and_b32_e32 v249, 1, v249
	v_lshl_or_b32 v250, v251, 10, v250
	v_lshl_or_b32 v250, v249, 7, v250
	global_load_dword v254, v250, s[98:99]
	s_or_b64 exec, exec, s[100:101]
	s_and_saveexec_b64 s[6:7], s[80:81]
	s_cbranch_execz .LBB0_815
	s_lshl_b32 s8, s33, 4
	s_ashr_i32 s9, s8, 31
	s_lshl_b64 s[0:1], s[8:9], 2
	v_readlane_b32 s2, v246, 2
	v_readlane_b32 s3, v246, 3
	s_add_u32 s0, s2, s0
	s_addc_u32 s1, s3, s1
	v_mov_b32_e32 v1, 0x1000
	global_load_dword v1, v1, s[0:1] sc1
	buffer_inv sc1
	s_add_u32 s12, s0, 0x1000
	s_addc_u32 s13, s1, 0
	s_waitcnt vmcnt(0)
	v_cmp_lt_u32_e32 vcc, 3, v1
	s_cbranch_vccnz .LBB0_800
	v_readlane_b32 s0, v246, 2
	v_readlane_b32 s1, v246, 3
	s_add_u32 s10, s0, 0x4200
	s_addc_u32 s11, s1, 0
	s_mov_b32 s0, 1
	v_mov_b32_e32 v1, 0
	s_branch .LBB0_790
